# combined work reductions: cross-half max only on the rescale path, running f32 row-sum pairs, up-front tile-0 fragment reads
# speedup vs baseline: 1.0111x; 1.0111x over previous
.LBB0_227:
	s_lshl_b32 s4, s59, 11
	s_and_b32 s5, s4, 0x1000000
	s_lshl_b32 s4, s36, 4
	s_and_b32 s28, s4, 0x700
	v_lshl_or_b32 v96, v148, 1, s28
	v_or_b32_e32 v96, s5, v96
	v_mov_b32_e32 v97, v209
	s_lshl_b32 s21, s21, 9
	s_mov_b32 s65, 2
	s_add_i32 s66, s8, 2
	s_mov_b32 s4, 1
	v_lshl_add_u64 v[174:175], v[170:171], 0, v[96:97]
	v_subrev_u32_e32 v204, s21, v194
	s_add_i32 s33, s61, s8
	s_mov_b32 s87, 0
	s_movk_i32 s68, 0xff00
	v_mov_b64_e32 v[136:137], 0
	v_mov_b64_e32 v[138:139], 0
	v_mov_b64_e32 v[140:141], 0
	v_mov_b64_e32 v[142:143], 0
	s_cmp_gt_u32 s56, 4
	s_cbranch_scc1 .Lqw4
	s_waitcnt vmcnt(5)
	s_branch .Lqwd

.Lnod_b1:
	s_cbranch_scc1 .LB1_skip
	v_max_f32_e32 v176, v96, v80
	v_max3_f32 v177, v81, v98, v82
	v_max3_f32 v176, v176, v97, v99
	v_max3_f32 v177, v177, v100, v84
	v_max3_f32 v176, v176, v83, v101
	v_max3_f32 v177, v177, v102, v86
	v_max3_f32 v176, v176, v85, v103
	v_max3_f32 v177, v177, v104, v88
	v_max3_f32 v176, v176, v87, v105
	v_max3_f32 v177, v177, v106, v90
	v_max3_f32 v176, v176, v89, v107
	v_max3_f32 v177, v177, v108, v92
	v_max3_f32 v176, v176, v91, v109
	v_max3_f32 v177, v177, v110, v94
	v_max3_f32 v176, v176, v93, v111
	v_max3_f32 v176, v176, v95, v177
	v_cmp_lt_f32_e32 vcc, 0x41000000, v176
	s_cbranch_vccnz .Lrs_b1
.Latt_b1_exp:
	v_exp_f32_e32 v96, v96
	v_exp_f32_e32 v97, v97
	v_exp_f32_e32 v176, v80
	v_exp_f32_e32 v177, v81
	v_exp_f32_e32 v98, v98
	v_exp_f32_e32 v99, v99
	v_exp_f32_e32 v178, v82
	v_exp_f32_e32 v179, v83
	v_exp_f32_e32 v100, v100
	v_exp_f32_e32 v101, v101
	v_exp_f32_e32 v180, v84
	v_exp_f32_e32 v181, v85
	v_exp_f32_e32 v102, v102
	v_exp_f32_e32 v103, v103
	v_exp_f32_e32 v182, v86
	v_exp_f32_e32 v183, v87
	v_exp_f32_e32 v104, v104
	v_exp_f32_e32 v105, v105
	v_exp_f32_e32 v184, v88
	v_exp_f32_e32 v185, v89
	v_exp_f32_e32 v106, v106
	v_exp_f32_e32 v107, v107
	v_exp_f32_e32 v186, v90
	v_exp_f32_e32 v187, v91
	v_exp_f32_e32 v108, v108
	v_exp_f32_e32 v109, v109
	v_exp_f32_e32 v188, v92
	v_exp_f32_e32 v189, v93
	v_exp_f32_e32 v110, v110
	v_exp_f32_e32 v111, v111
	v_exp_f32_e32 v190, v94
	v_exp_f32_e32 v191, v95
	v_cvt_pk_bf16_f32 v80, v96, v97
	v_cvt_pk_bf16_f32 v81, v98, v99
	v_cvt_pk_bf16_f32 v82, v100, v101
	v_cvt_pk_bf16_f32 v83, v102, v103
	v_cvt_pk_bf16_f32 v84, v104, v105
	v_cvt_pk_bf16_f32 v85, v106, v107
	v_cvt_pk_bf16_f32 v86, v108, v109
	v_cvt_pk_bf16_f32 v87, v110, v111
	v_cvt_pk_bf16_f32 v88, v176, v177
	v_cvt_pk_bf16_f32 v89, v178, v179
	v_cvt_pk_bf16_f32 v90, v180, v181
	v_cvt_pk_bf16_f32 v91, v182, v183
	v_cvt_pk_bf16_f32 v92, v184, v185
	v_cvt_pk_bf16_f32 v93, v186, v187
	v_cvt_pk_bf16_f32 v94, v188, v189
	v_cvt_pk_bf16_f32 v95, v190, v191
	v_pk_add_f32 v[96:97], v[96:97], v[100:101]
	v_pk_add_f32 v[98:99], v[98:99], v[102:103]
	v_pk_add_f32 v[176:177], v[176:177], v[180:181]
	v_pk_add_f32 v[178:179], v[178:179], v[182:183]
	v_pk_add_f32 v[96:97], v[96:97], v[104:105]
	v_pk_add_f32 v[98:99], v[98:99], v[106:107]
	v_pk_add_f32 v[176:177], v[176:177], v[184:185]
	v_pk_add_f32 v[178:179], v[178:179], v[186:187]
	v_pk_add_f32 v[96:97], v[96:97], v[108:109]
	v_pk_add_f32 v[98:99], v[98:99], v[110:111]
	v_pk_add_f32 v[176:177], v[176:177], v[188:189]
	v_pk_add_f32 v[178:179], v[178:179], v[190:191]
	v_pk_add_f32 v[136:137], v[136:137], v[96:97]
	v_pk_add_f32 v[138:139], v[138:139], v[98:99]
	v_pk_add_f32 v[140:141], v[140:141], v[176:177]
	v_pk_add_f32 v[142:143], v[142:143], v[178:179]
	s_cmp_ge_i32 s65, s86
	s_cbranch_scc1 .LB1_pvonly
	v_add_u32_e32 v205, 0x5000, v165
	v_add_u32_e32 v206, 0x20400, v192
	s_cmp_lt_u32 s65, s87
	s_cbranch_scc0 .Lw0_b1
	s_waitcnt vmcnt(5) lgkmcnt(0)

.Latt_b2_exp:
	v_exp_f32_e32 v96, v96
	v_exp_f32_e32 v97, v97
	v_exp_f32_e32 v176, v80
	v_exp_f32_e32 v177, v81
	v_exp_f32_e32 v98, v98
	v_exp_f32_e32 v99, v99
	v_exp_f32_e32 v178, v82
	v_exp_f32_e32 v179, v83
	v_exp_f32_e32 v100, v100
	v_exp_f32_e32 v101, v101
	v_exp_f32_e32 v180, v84
	v_exp_f32_e32 v181, v85
	v_exp_f32_e32 v102, v102
	v_exp_f32_e32 v103, v103
	v_exp_f32_e32 v182, v86
	v_exp_f32_e32 v183, v87
	v_exp_f32_e32 v104, v104
	v_exp_f32_e32 v105, v105
	v_exp_f32_e32 v184, v88
	v_exp_f32_e32 v185, v89
	v_exp_f32_e32 v106, v106
	v_exp_f32_e32 v107, v107
	v_exp_f32_e32 v186, v90
	v_exp_f32_e32 v187, v91
	v_exp_f32_e32 v108, v108
	v_exp_f32_e32 v109, v109
	v_exp_f32_e32 v188, v92
	v_exp_f32_e32 v189, v93
	v_exp_f32_e32 v110, v110
	v_exp_f32_e32 v111, v111
	v_exp_f32_e32 v190, v94
	v_exp_f32_e32 v191, v95
	v_cvt_pk_bf16_f32 v80, v96, v97
	v_cvt_pk_bf16_f32 v81, v98, v99
	v_cvt_pk_bf16_f32 v82, v100, v101
	v_cvt_pk_bf16_f32 v83, v102, v103
	v_cvt_pk_bf16_f32 v84, v104, v105
	v_cvt_pk_bf16_f32 v85, v106, v107
	v_cvt_pk_bf16_f32 v86, v108, v109
	v_cvt_pk_bf16_f32 v87, v110, v111
	v_cvt_pk_bf16_f32 v88, v176, v177
	v_cvt_pk_bf16_f32 v89, v178, v179
	v_cvt_pk_bf16_f32 v90, v180, v181
	v_cvt_pk_bf16_f32 v91, v182, v183
	v_cvt_pk_bf16_f32 v92, v184, v185
	v_cvt_pk_bf16_f32 v93, v186, v187
	v_cvt_pk_bf16_f32 v94, v188, v189
	v_cvt_pk_bf16_f32 v95, v190, v191
	v_pk_add_f32 v[96:97], v[96:97], v[100:101]
	v_pk_add_f32 v[98:99], v[98:99], v[102:103]
	v_pk_add_f32 v[176:177], v[176:177], v[180:181]
	v_pk_add_f32 v[178:179], v[178:179], v[182:183]
	v_pk_add_f32 v[96:97], v[96:97], v[104:105]
	v_pk_add_f32 v[98:99], v[98:99], v[106:107]
	v_pk_add_f32 v[176:177], v[176:177], v[184:185]
	v_pk_add_f32 v[178:179], v[178:179], v[186:187]
	v_pk_add_f32 v[96:97], v[96:97], v[108:109]
	v_pk_add_f32 v[98:99], v[98:99], v[110:111]
	v_pk_add_f32 v[176:177], v[176:177], v[188:189]
	v_pk_add_f32 v[178:179], v[178:179], v[190:191]
	v_pk_add_f32 v[136:137], v[136:137], v[96:97]
	v_pk_add_f32 v[138:139], v[138:139], v[98:99]
	v_pk_add_f32 v[140:141], v[140:141], v[176:177]
	v_pk_add_f32 v[142:143], v[142:143], v[178:179]
	s_cmp_ge_i32 s65, s86
	s_cbranch_scc1 .LB2_pvonly
	v_add_u32_e32 v205, 0xa000, v165
	v_add_u32_e32 v206, 0x0, v192
	s_cmp_lt_u32 s65, s87
	s_cbranch_scc0 .Lw0_b2
	s_waitcnt vmcnt(5) lgkmcnt(0)

.Latt_b0_exp:
	v_exp_f32_e32 v96, v96
	v_exp_f32_e32 v97, v97
	v_exp_f32_e32 v176, v80
	v_exp_f32_e32 v177, v81
	v_exp_f32_e32 v98, v98
	v_exp_f32_e32 v99, v99
	v_exp_f32_e32 v178, v82
	v_exp_f32_e32 v179, v83
	v_exp_f32_e32 v100, v100
	v_exp_f32_e32 v101, v101
	v_exp_f32_e32 v180, v84
	v_exp_f32_e32 v181, v85
	v_exp_f32_e32 v102, v102
	v_exp_f32_e32 v103, v103
	v_exp_f32_e32 v182, v86
	v_exp_f32_e32 v183, v87
	v_exp_f32_e32 v104, v104
	v_exp_f32_e32 v105, v105
	v_exp_f32_e32 v184, v88
	v_exp_f32_e32 v185, v89
	v_exp_f32_e32 v106, v106
	v_exp_f32_e32 v107, v107
	v_exp_f32_e32 v186, v90
	v_exp_f32_e32 v187, v91
	v_exp_f32_e32 v108, v108
	v_exp_f32_e32 v109, v109
	v_exp_f32_e32 v188, v92
	v_exp_f32_e32 v189, v93
	v_exp_f32_e32 v110, v110
	v_exp_f32_e32 v111, v111
	v_exp_f32_e32 v190, v94
	v_exp_f32_e32 v191, v95
	v_cvt_pk_bf16_f32 v80, v96, v97
	v_cvt_pk_bf16_f32 v81, v98, v99
	v_cvt_pk_bf16_f32 v82, v100, v101
	v_cvt_pk_bf16_f32 v83, v102, v103
	v_cvt_pk_bf16_f32 v84, v104, v105
	v_cvt_pk_bf16_f32 v85, v106, v107
	v_cvt_pk_bf16_f32 v86, v108, v109
	v_cvt_pk_bf16_f32 v87, v110, v111
	v_cvt_pk_bf16_f32 v88, v176, v177
	v_cvt_pk_bf16_f32 v89, v178, v179
	v_cvt_pk_bf16_f32 v90, v180, v181
	v_cvt_pk_bf16_f32 v91, v182, v183
	v_cvt_pk_bf16_f32 v92, v184, v185
	v_cvt_pk_bf16_f32 v93, v186, v187
	v_cvt_pk_bf16_f32 v94, v188, v189
	v_cvt_pk_bf16_f32 v95, v190, v191
	v_pk_add_f32 v[96:97], v[96:97], v[100:101]
	v_pk_add_f32 v[98:99], v[98:99], v[102:103]
	v_pk_add_f32 v[176:177], v[176:177], v[180:181]
	v_pk_add_f32 v[178:179], v[178:179], v[182:183]
	v_pk_add_f32 v[96:97], v[96:97], v[104:105]
	v_pk_add_f32 v[98:99], v[98:99], v[106:107]
	v_pk_add_f32 v[176:177], v[176:177], v[184:185]
	v_pk_add_f32 v[178:179], v[178:179], v[186:187]
	v_pk_add_f32 v[96:97], v[96:97], v[108:109]
	v_pk_add_f32 v[98:99], v[98:99], v[110:111]
	v_pk_add_f32 v[176:177], v[176:177], v[188:189]
	v_pk_add_f32 v[178:179], v[178:179], v[190:191]
	v_pk_add_f32 v[136:137], v[136:137], v[96:97]
	v_pk_add_f32 v[138:139], v[138:139], v[98:99]
	v_pk_add_f32 v[140:141], v[140:141], v[176:177]
	v_pk_add_f32 v[142:143], v[142:143], v[178:179]
	s_cmp_ge_i32 s65, s86
	s_cbranch_scc1 .LB0_pvonly
	v_add_u32_e32 v205, 0x0, v165
	v_add_u32_e32 v206, 0x4400, v192
	s_cmp_lt_u32 s65, s87
	s_cbranch_scc0 .Lw0_b0
	s_waitcnt vmcnt(5) lgkmcnt(0)

.Lnod_a1:
	v_max_f32_e32 v176, v96, v80
	v_max3_f32 v177, v81, v98, v82
	v_max3_f32 v176, v176, v97, v99
	v_max3_f32 v177, v177, v100, v84
	v_max3_f32 v176, v176, v83, v101
	v_max3_f32 v177, v177, v102, v86
	v_max3_f32 v176, v176, v85, v103
	v_max3_f32 v177, v177, v104, v88
	v_max3_f32 v176, v176, v87, v105
	v_max3_f32 v177, v177, v106, v90
	v_max3_f32 v176, v176, v89, v107
	v_max3_f32 v177, v177, v108, v92
	v_max3_f32 v176, v176, v91, v109
	v_max3_f32 v177, v177, v110, v94
	v_max3_f32 v176, v176, v93, v111
	v_max3_f32 v176, v176, v95, v177
	v_cmp_lt_f32_e32 vcc, 0x41000000, v176
	s_cbranch_vccnz .Lrs_a1

.Lrs_b1:
	v_mov_b32_e32 v177, v176
	s_nop 1
	v_permlane32_swap_b32_e32 v176, v177
	v_max_f32_e32 v176, v176, v177
	v_max_f32_e32 v64, v176, v176
	v_max_f32_e32 v66, 0, v64
	v_exp_f32_e64 v176, -v66
	v_add_f32_e32 v173, v173, v66
	v_xor_b32_e32 v64, 0x80000000, v173
	v_pk_add_f32 v[96:97], v[96:97], v[66:67] op_sel_hi:[1,0] neg_lo:[0,1] neg_hi:[0,1]
	v_pk_add_f32 v[80:81], v[80:81], v[66:67] op_sel_hi:[1,0] neg_lo:[0,1] neg_hi:[0,1]
	v_pk_add_f32 v[98:99], v[98:99], v[66:67] op_sel_hi:[1,0] neg_lo:[0,1] neg_hi:[0,1]
	v_pk_add_f32 v[82:83], v[82:83], v[66:67] op_sel_hi:[1,0] neg_lo:[0,1] neg_hi:[0,1]
	v_pk_add_f32 v[100:101], v[100:101], v[66:67] op_sel_hi:[1,0] neg_lo:[0,1] neg_hi:[0,1]
	v_pk_add_f32 v[84:85], v[84:85], v[66:67] op_sel_hi:[1,0] neg_lo:[0,1] neg_hi:[0,1]
	v_pk_add_f32 v[102:103], v[102:103], v[66:67] op_sel_hi:[1,0] neg_lo:[0,1] neg_hi:[0,1]
	v_pk_add_f32 v[86:87], v[86:87], v[66:67] op_sel_hi:[1,0] neg_lo:[0,1] neg_hi:[0,1]
	v_pk_add_f32 v[104:105], v[104:105], v[66:67] op_sel_hi:[1,0] neg_lo:[0,1] neg_hi:[0,1]
	v_pk_add_f32 v[88:89], v[88:89], v[66:67] op_sel_hi:[1,0] neg_lo:[0,1] neg_hi:[0,1]
	v_pk_add_f32 v[106:107], v[106:107], v[66:67] op_sel_hi:[1,0] neg_lo:[0,1] neg_hi:[0,1]
	v_pk_add_f32 v[90:91], v[90:91], v[66:67] op_sel_hi:[1,0] neg_lo:[0,1] neg_hi:[0,1]
	v_pk_add_f32 v[108:109], v[108:109], v[66:67] op_sel_hi:[1,0] neg_lo:[0,1] neg_hi:[0,1]
	v_pk_add_f32 v[92:93], v[92:93], v[66:67] op_sel_hi:[1,0] neg_lo:[0,1] neg_hi:[0,1]
	v_pk_add_f32 v[110:111], v[110:111], v[66:67] op_sel_hi:[1,0] neg_lo:[0,1] neg_hi:[0,1]
	v_pk_add_f32 v[94:95], v[94:95], v[66:67] op_sel_hi:[1,0] neg_lo:[0,1] neg_hi:[0,1]
	v_mov_b32_e32 v65, v64
	v_mov_b32_e32 v66, v64
	v_mov_b32_e32 v67, v64
	v_mov_b32_e32 v68, v64
	v_mov_b32_e32 v69, v64
	v_mov_b32_e32 v70, v64
	v_mov_b32_e32 v71, v64
	v_mov_b32_e32 v72, v64
	v_mov_b32_e32 v73, v64
	v_mov_b32_e32 v74, v64
	v_mov_b32_e32 v75, v64
	v_mov_b32_e32 v76, v64
	v_mov_b32_e32 v77, v64
	v_mov_b32_e32 v78, v64
	v_mov_b32_e32 v79, v64
	v_pk_mul_f32 v[46:47], v[46:47], v[176:177] op_sel_hi:[1,0]
	v_pk_mul_f32 v[44:45], v[44:45], v[176:177] op_sel_hi:[1,0]
	v_pk_mul_f32 v[42:43], v[42:43], v[176:177] op_sel_hi:[1,0]
	v_pk_mul_f32 v[40:41], v[40:41], v[176:177] op_sel_hi:[1,0]
	v_pk_mul_f32 v[38:39], v[38:39], v[176:177] op_sel_hi:[1,0]
	v_pk_mul_f32 v[36:37], v[36:37], v[176:177] op_sel_hi:[1,0]
	v_pk_mul_f32 v[34:35], v[34:35], v[176:177] op_sel_hi:[1,0]
	v_pk_mul_f32 v[32:33], v[32:33], v[176:177] op_sel_hi:[1,0]
	v_pk_mul_f32 v[30:31], v[30:31], v[176:177] op_sel_hi:[1,0]
	v_pk_mul_f32 v[28:29], v[28:29], v[176:177] op_sel_hi:[1,0]
	v_pk_mul_f32 v[26:27], v[26:27], v[176:177] op_sel_hi:[1,0]
	v_pk_mul_f32 v[24:25], v[24:25], v[176:177] op_sel_hi:[1,0]
	v_pk_mul_f32 v[22:23], v[22:23], v[176:177] op_sel_hi:[1,0]
	v_pk_mul_f32 v[20:21], v[20:21], v[176:177] op_sel_hi:[1,0]
	v_pk_mul_f32 v[18:19], v[18:19], v[176:177] op_sel_hi:[1,0]
	v_pk_mul_f32 v[16:17], v[16:17], v[176:177] op_sel_hi:[1,0]
	v_pk_mul_f32 v[14:15], v[14:15], v[176:177] op_sel_hi:[1,0]
	v_pk_mul_f32 v[12:13], v[12:13], v[176:177] op_sel_hi:[1,0]
	v_pk_mul_f32 v[10:11], v[10:11], v[176:177] op_sel_hi:[1,0]
	v_pk_mul_f32 v[8:9], v[8:9], v[176:177] op_sel_hi:[1,0]
	v_pk_mul_f32 v[6:7], v[6:7], v[176:177] op_sel_hi:[1,0]
	v_pk_mul_f32 v[4:5], v[4:5], v[176:177] op_sel_hi:[1,0]
	v_pk_mul_f32 v[2:3], v[2:3], v[176:177] op_sel_hi:[1,0]
	v_pk_mul_f32 v[0:1], v[0:1], v[176:177] op_sel_hi:[1,0]
	v_pk_mul_f32 v[62:63], v[62:63], v[176:177] op_sel_hi:[1,0]
	v_pk_mul_f32 v[60:61], v[60:61], v[176:177] op_sel_hi:[1,0]
	v_pk_mul_f32 v[58:59], v[58:59], v[176:177] op_sel_hi:[1,0]
	v_pk_mul_f32 v[56:57], v[56:57], v[176:177] op_sel_hi:[1,0]
	v_pk_mul_f32 v[54:55], v[54:55], v[176:177] op_sel_hi:[1,0]
	v_pk_mul_f32 v[52:53], v[52:53], v[176:177] op_sel_hi:[1,0]
	v_pk_mul_f32 v[50:51], v[50:51], v[176:177] op_sel_hi:[1,0]
	v_pk_mul_f32 v[48:49], v[48:49], v[176:177] op_sel_hi:[1,0]
	v_mul_f32_e32 v172, v172, v176
	v_pk_mul_f32 v[136:137], v[136:137], v[176:177] op_sel_hi:[1,0]
	v_pk_mul_f32 v[138:139], v[138:139], v[176:177] op_sel_hi:[1,0]
	v_pk_mul_f32 v[140:141], v[140:141], v[176:177] op_sel_hi:[1,0]
	v_pk_mul_f32 v[142:143], v[142:143], v[176:177] op_sel_hi:[1,0]
	s_branch .Latt_b1_exp

.LBB0_243:
	v_pk_add_f32 v[136:137], v[136:137], v[138:139]
	v_pk_add_f32 v[140:141], v[140:141], v[142:143]
	s_nop 0
	v_pk_add_f32 v[136:137], v[136:137], v[140:141]
	s_nop 0
	v_add_f32_e32 v136, v136, v137
	v_add_f32_e32 v172, v172, v136
	s_and_b64 vcc, exec, s[16:17]
	s_cbranch_vccz .LBB0_245
	s_mul_i32 s4, s69, 0x5000
	v_add_u32_e32 v96, s4, v165
	ds_read_b64_tr_b16 v[64:65], v96 offset:34816
	ds_read_b64_tr_b16 v[66:67], v96 offset:37376
	ds_read_b64_tr_b16 v[68:69], v96 offset:39936
	ds_read_b64_tr_b16 v[70:71], v96 offset:42496
	ds_read_b64_tr_b16 v[72:73], v96 offset:45056
	ds_read_b64_tr_b16 v[74:75], v96 offset:47616
	ds_read_b64_tr_b16 v[76:77], v96 offset:50176
	ds_read_b64_tr_b16 v[78:79], v96 offset:52736
	s_setprio 1
	s_waitcnt lgkmcnt(6)
	v_mfma_f32_32x32x16_bf16 v[32:47], v[64:67], v[80:83], v[32:47]
	s_setprio 0
	ds_read_b64_tr_b16 v[64:65], v96 offset:34880
	ds_read_b64_tr_b16 v[66:67], v96 offset:37440
	s_setprio 1
	s_waitcnt lgkmcnt(6)
	v_mfma_f32_32x32x16_bf16 v[32:47], v[68:71], v[84:87], v[32:47]
	s_setprio 0
	ds_read_b64_tr_b16 v[68:69], v96 offset:40000
	ds_read_b64_tr_b16 v[70:71], v96 offset:42560
	s_setprio 1
	s_waitcnt lgkmcnt(6)
	v_mfma_f32_32x32x16_bf16 v[32:47], v[72:75], v[88:91], v[32:47]
	s_setprio 0
	ds_read_b64_tr_b16 v[72:73], v96 offset:45120
	ds_read_b64_tr_b16 v[74:75], v96 offset:47680
	s_setprio 1
	s_waitcnt lgkmcnt(6)
	v_mfma_f32_32x32x16_bf16 v[32:47], v[76:79], v[92:95], v[32:47]
	s_setprio 0
	ds_read_b64_tr_b16 v[76:77], v96 offset:50240
	ds_read_b64_tr_b16 v[78:79], v96 offset:52800
	s_setprio 1
	s_waitcnt lgkmcnt(6)
	v_mfma_f32_32x32x16_bf16 v[16:31], v[64:67], v[80:83], v[16:31]
	s_setprio 0
	ds_read_b64_tr_b16 v[64:65], v96 offset:34944
	ds_read_b64_tr_b16 v[66:67], v96 offset:37504
	s_setprio 1
	s_waitcnt lgkmcnt(6)
	v_mfma_f32_32x32x16_bf16 v[16:31], v[68:71], v[84:87], v[16:31]
	s_setprio 0
	ds_read_b64_tr_b16 v[68:69], v96 offset:40064
	ds_read_b64_tr_b16 v[70:71], v96 offset:42624
	s_setprio 1
	s_waitcnt lgkmcnt(6)
	v_mfma_f32_32x32x16_bf16 v[16:31], v[72:75], v[88:91], v[16:31]
	s_setprio 0
	ds_read_b64_tr_b16 v[72:73], v96 offset:45184
	ds_read_b64_tr_b16 v[74:75], v96 offset:47744
	s_setprio 1
	s_waitcnt lgkmcnt(6)
	v_mfma_f32_32x32x16_bf16 v[16:31], v[76:79], v[92:95], v[16:31]
	s_setprio 0
	ds_read_b64_tr_b16 v[76:77], v96 offset:50304
	ds_read_b64_tr_b16 v[78:79], v96 offset:52864
	s_setprio 1
	s_waitcnt lgkmcnt(6)
	v_mfma_f32_32x32x16_bf16 v[0:15], v[64:67], v[80:83], v[0:15]
	s_setprio 0
	ds_read_b64_tr_b16 v[64:65], v96 offset:35008
	ds_read_b64_tr_b16 v[66:67], v96 offset:37568
	s_setprio 1
	s_waitcnt lgkmcnt(6)
	v_mfma_f32_32x32x16_bf16 v[0:15], v[68:71], v[84:87], v[0:15]
	s_setprio 0
	ds_read_b64_tr_b16 v[68:69], v96 offset:40128
	ds_read_b64_tr_b16 v[70:71], v96 offset:42688
	s_setprio 1
	s_waitcnt lgkmcnt(6)
	v_mfma_f32_32x32x16_bf16 v[0:15], v[72:75], v[88:91], v[0:15]
	s_setprio 0
	ds_read_b64_tr_b16 v[72:73], v96 offset:45248
	ds_read_b64_tr_b16 v[74:75], v96 offset:47808
	s_setprio 1
	s_waitcnt lgkmcnt(6)
	v_mfma_f32_32x32x16_bf16 v[0:15], v[76:79], v[92:95], v[0:15]
	s_setprio 0
	ds_read_b64_tr_b16 v[76:77], v96 offset:50368
	ds_read_b64_tr_b16 v[78:79], v96 offset:52928
	s_setprio 1
	s_waitcnt lgkmcnt(6)
	v_mfma_f32_32x32x16_bf16 v[48:63], v[64:67], v[80:83], v[48:63]
	s_setprio 0
	s_setprio 1
	s_waitcnt lgkmcnt(4)
	v_mfma_f32_32x32x16_bf16 v[48:63], v[68:71], v[84:87], v[48:63]
	s_setprio 0
	s_setprio 1
	s_waitcnt lgkmcnt(2)
	v_mfma_f32_32x32x16_bf16 v[48:63], v[72:75], v[88:91], v[48:63]
	s_setprio 0
	s_setprio 1
	s_waitcnt lgkmcnt(0)
	v_mfma_f32_32x32x16_bf16 v[48:63], v[76:79], v[92:95], v[48:63]
	s_setprio 0
